# GEMM epilogues: next slice's LDS write issued behind the current slice's read-back (counted lgkmcnt), one LDS latency less per step
# baseline (speedup 1.0000x reference)
; __device__ __forceinline__ unsigned pk2(float lo, float hi) { const v2f_t f = {lo, hi}; const v2bf_t b = __builtin_convertvector(f, v2bf_t); return __builtin_bit_cast(unsigned, b); }
;     __device__ __forceinline__ void operator()(const f32x4 (&acc)[2][2][4][2], const Unit& u, int wr, int wc, int fr, int fq) const {
;     ...
;         } else if (u.pn < 16) {
;             bf16_t* base; int ld, colt;
;             if (u.pn < 2) { base = pk; ld = 512; colt = u.pn * 256; }
;             else if (u.pn < 8) { base = pq; ld = 512; colt = (u.pn - 6) * 256; }
;             else if (u.pn < 12) { base = pg; ld = 1024; colt = (u.pn - 8) * 256; }
;             else { base = pu; ld = 1024; colt = (u.pn - 12) * 256; }
;             const int col0 = colt + wc * 32 + 8 * fq;
; #pragma unroll
;             for (int ai = 0; ai < 2; ++ai)
; #pragma unroll
;                 for (int m = 0; m < 4; ++m) { bf16_t* rowp = base + (size_t)(row0 + ai * 128 + m * 16) * ld + col0;
; #pragma unroll
;                     for (int bj = 0; bj < 2; ++bj) { const f32x4 v0 = acc[ai][bj][m][0], v1 = acc[ai][bj][m][1];
;                         u32x4 w; w.x = pk2(v0[0], v0[1]); w.y = pk2(v0[2], v0[3]); w.z = pk2(v1[0], v1[1]); w.w = pk2(v1[2], v1[3]);
;                         *(u32x4*)(rowp + bj * 128) = w; } }
.LBB0_255:
	v_and_b32_e32 v157, 15, v194
	v_bfe_u32 v158, v194, 6, 2
	v_bfe_u32 v159, v194, 4, 2
	v_bfe_u32 v156, v194, 8, 1
	v_lshlrev_b32_e32 v156, 4, v156
	v_add_u32_e32 v156, v156, v157
	v_mul_u32_u24_e32 v186, 0x110, v156
	v_lshl_add_u32 v186, v158, 6, v186
	v_lshl_add_u32 v186, v159, 4, v186
	v_add_u32_e32 v186, 0x23410, v186
	v_lshrrev_b32_e32 v160, 6, v194
	v_lshl_add_u32 v160, v160, 2, v159
	v_mul_u32_u24_e32 v187, 0x110, v160
	v_lshl_add_u32 v187, v157, 4, v187
	v_add_u32_e32 v187, 0x23410, v187
	v_sub_u32_e32 v156, v142, v157
	v_lshl_add_u32 v156, v158, 2, v156
	v_add_u32_e32 v156, v156, v159
	v_mul_lo_u32 v156, v156, s48
	v_lshlrev_b32_e32 v156, 1, v156
	v_lshlrev_b32_e32 v160, 4, v157
	v_lshl_add_u32 v160, s39, 1, v160
	v_add_u32_e32 v156, v156, v160
	v_mov_b32_e32 v157, 0
	v_lshl_add_u64 v[188:189], s[50:51], 0, v[156:157]
	s_mov_b32 s99, 0
	v_cvt_pk_bf16_f32 v174, v126, v127
	v_cvt_pk_bf16_f32 v175, v128, v129
	v_cvt_pk_bf16_f32 v176, v122, v123
	v_cvt_pk_bf16_f32 v177, v124, v125
	ds_write_b128 v186, v[174:177]
	s_waitcnt lgkmcnt(0)
	s_barrier
	ds_read_b128 v[178:181], v187
	s_mul_i32 s98, s48, 0
	v_lshl_add_u64 v[190:191], v[188:189], 0, s[98:99]
	v_cvt_pk_bf16_f32 v174, v118, v119
	v_cvt_pk_bf16_f32 v175, v120, v121
	v_cvt_pk_bf16_f32 v176, v114, v115
	v_cvt_pk_bf16_f32 v177, v116, v117
	ds_write_b128 v186, v[174:177] offset:8704
	s_waitcnt lgkmcnt(1)
	global_store_dwordx4 v[190:191], v[178:181], off
	s_waitcnt lgkmcnt(0)
	s_barrier
	ds_read_b128 v[182:185], v187 offset:8704
	v_cvt_pk_bf16_f32 v174, v110, v111
	v_cvt_pk_bf16_f32 v175, v112, v113
	v_cvt_pk_bf16_f32 v176, v106, v107
	v_cvt_pk_bf16_f32 v177, v108, v109
	ds_write_b128 v186, v[174:177]
	s_waitcnt lgkmcnt(1)
	global_store_dwordx4 v[190:191], v[182:185], off offset:256
	s_waitcnt lgkmcnt(0)
	s_barrier
	ds_read_b128 v[178:181], v187
	s_mul_i32 s98, s48, 32
	v_lshl_add_u64 v[190:191], v[188:189], 0, s[98:99]
	v_cvt_pk_bf16_f32 v174, v102, v103
	v_cvt_pk_bf16_f32 v175, v104, v105
	v_cvt_pk_bf16_f32 v176, v98, v99
	v_cvt_pk_bf16_f32 v177, v100, v101
	ds_write_b128 v186, v[174:177] offset:8704
	s_waitcnt lgkmcnt(1)
	global_store_dwordx4 v[190:191], v[178:181], off
	s_waitcnt lgkmcnt(0)
	s_barrier
	ds_read_b128 v[182:185], v187 offset:8704
	v_cvt_pk_bf16_f32 v174, v94, v95
	v_cvt_pk_bf16_f32 v175, v96, v97
	v_cvt_pk_bf16_f32 v176, v90, v91
	v_cvt_pk_bf16_f32 v177, v92, v93
	ds_write_b128 v186, v[174:177]
	s_waitcnt lgkmcnt(1)
	global_store_dwordx4 v[190:191], v[182:185], off offset:256
	s_waitcnt lgkmcnt(0)
	s_barrier
	ds_read_b128 v[178:181], v187
	s_mul_i32 s98, s48, 64
	v_lshl_add_u64 v[190:191], v[188:189], 0, s[98:99]
	v_cvt_pk_bf16_f32 v174, v86, v87
	v_cvt_pk_bf16_f32 v175, v88, v89
	v_cvt_pk_bf16_f32 v176, v82, v83
	v_cvt_pk_bf16_f32 v177, v84, v85
	ds_write_b128 v186, v[174:177] offset:8704
	s_waitcnt lgkmcnt(1)
	global_store_dwordx4 v[190:191], v[178:181], off
	s_waitcnt lgkmcnt(0)
	s_barrier
	ds_read_b128 v[182:185], v187 offset:8704
	v_cvt_pk_bf16_f32 v174, v78, v79
	v_cvt_pk_bf16_f32 v175, v80, v81
	v_cvt_pk_bf16_f32 v176, v74, v75
	v_cvt_pk_bf16_f32 v177, v76, v77
	ds_write_b128 v186, v[174:177]
	s_waitcnt lgkmcnt(1)
	global_store_dwordx4 v[190:191], v[182:185], off offset:256
	s_waitcnt lgkmcnt(0)
	s_barrier
	ds_read_b128 v[178:181], v187
	s_mul_i32 s98, s48, 96
	v_lshl_add_u64 v[190:191], v[188:189], 0, s[98:99]
	v_cvt_pk_bf16_f32 v174, v70, v71
	v_cvt_pk_bf16_f32 v175, v72, v73
	v_cvt_pk_bf16_f32 v176, v66, v67
	v_cvt_pk_bf16_f32 v177, v68, v69
	ds_write_b128 v186, v[174:177] offset:8704
	s_waitcnt lgkmcnt(1)
	global_store_dwordx4 v[190:191], v[178:181], off
	s_waitcnt lgkmcnt(0)
	s_barrier
	ds_read_b128 v[182:185], v187 offset:8704
	v_cvt_pk_bf16_f32 v174, v60, v61
	v_cvt_pk_bf16_f32 v175, v62, v63
	v_cvt_pk_bf16_f32 v176, v56, v57
	v_cvt_pk_bf16_f32 v177, v58, v59
	ds_write_b128 v186, v[174:177]
	s_waitcnt lgkmcnt(1)
	global_store_dwordx4 v[190:191], v[182:185], off offset:256
	s_waitcnt lgkmcnt(0)
	s_barrier
	ds_read_b128 v[178:181], v187
	s_mul_i32 s98, s48, 256
	v_lshl_add_u64 v[190:191], v[188:189], 0, s[98:99]
	v_cvt_pk_bf16_f32 v174, v52, v53
	v_cvt_pk_bf16_f32 v175, v54, v55
	v_cvt_pk_bf16_f32 v176, v48, v49
	v_cvt_pk_bf16_f32 v177, v50, v51
	ds_write_b128 v186, v[174:177] offset:8704
	s_waitcnt lgkmcnt(1)
	global_store_dwordx4 v[190:191], v[178:181], off
	s_waitcnt lgkmcnt(0)
	s_barrier
	ds_read_b128 v[182:185], v187 offset:8704
	v_cvt_pk_bf16_f32 v174, v44, v45
	v_cvt_pk_bf16_f32 v175, v46, v47
	v_cvt_pk_bf16_f32 v176, v40, v41
	v_cvt_pk_bf16_f32 v177, v42, v43
	ds_write_b128 v186, v[174:177]
	s_waitcnt lgkmcnt(1)
	global_store_dwordx4 v[190:191], v[182:185], off offset:256
	s_waitcnt lgkmcnt(0)
	s_barrier
	ds_read_b128 v[178:181], v187
	s_mul_i32 s98, s48, 288
	v_lshl_add_u64 v[190:191], v[188:189], 0, s[98:99]
	v_cvt_pk_bf16_f32 v174, v36, v37
	v_cvt_pk_bf16_f32 v175, v38, v39
	v_cvt_pk_bf16_f32 v176, v32, v33
	v_cvt_pk_bf16_f32 v177, v34, v35
	ds_write_b128 v186, v[174:177] offset:8704
	s_waitcnt lgkmcnt(1)
	global_store_dwordx4 v[190:191], v[178:181], off
	s_waitcnt lgkmcnt(0)
	s_barrier
	ds_read_b128 v[182:185], v187 offset:8704
	v_cvt_pk_bf16_f32 v174, v28, v29
	v_cvt_pk_bf16_f32 v175, v30, v31
	v_cvt_pk_bf16_f32 v176, v24, v25
	v_cvt_pk_bf16_f32 v177, v26, v27
	ds_write_b128 v186, v[174:177]
	s_waitcnt lgkmcnt(1)
	global_store_dwordx4 v[190:191], v[182:185], off offset:256
	s_waitcnt lgkmcnt(0)
	s_barrier
	ds_read_b128 v[178:181], v187
	s_mul_i32 s98, s48, 320
	v_lshl_add_u64 v[190:191], v[188:189], 0, s[98:99]
	v_cvt_pk_bf16_f32 v174, v20, v21
	v_cvt_pk_bf16_f32 v175, v22, v23
	v_cvt_pk_bf16_f32 v176, v16, v17
	v_cvt_pk_bf16_f32 v177, v18, v19
	ds_write_b128 v186, v[174:177] offset:8704
	s_waitcnt lgkmcnt(1)
	global_store_dwordx4 v[190:191], v[178:181], off
	s_waitcnt lgkmcnt(0)
	s_barrier
	ds_read_b128 v[182:185], v187 offset:8704
	v_cvt_pk_bf16_f32 v174, v12, v13
	v_cvt_pk_bf16_f32 v175, v14, v15
	v_cvt_pk_bf16_f32 v176, v8, v9
	v_cvt_pk_bf16_f32 v177, v10, v11
	ds_write_b128 v186, v[174:177]
	s_waitcnt lgkmcnt(1)
	global_store_dwordx4 v[190:191], v[182:185], off offset:256
	s_waitcnt lgkmcnt(0)
	s_barrier
	ds_read_b128 v[178:181], v187
	s_mul_i32 s98, s48, 352
	v_lshl_add_u64 v[190:191], v[188:189], 0, s[98:99]
	v_cvt_pk_bf16_f32 v174, v4, v5
	v_cvt_pk_bf16_f32 v175, v6, v7
	v_cvt_pk_bf16_f32 v176, v0, v1
	v_cvt_pk_bf16_f32 v177, v2, v3
	ds_write_b128 v186, v[174:177] offset:8704
	s_waitcnt lgkmcnt(1)
	global_store_dwordx4 v[190:191], v[178:181], off
	s_waitcnt lgkmcnt(0)
	s_barrier
	ds_read_b128 v[182:185], v187 offset:8704
	s_waitcnt lgkmcnt(0)
	global_store_dwordx4 v[190:191], v[182:185], off offset:256

; __device__ __forceinline__ unsigned pk2(float lo, float hi) { const v2f_t f = {lo, hi}; const v2bf_t b = __builtin_convertvector(f, v2bf_t); return __builtin_bit_cast(unsigned, b); }
;     __device__ __forceinline__ void operator()(const f32x4 (&acc)[2][2][4][2], const Unit& u, int wr, int wc, int fr, int fq) const {
;     ...
;         const int mr = u.pm < 64 ? (u.pm >> 4) : 4;
;         const float* gp = gate + (size_t)mr * 6 * D + col0;
;         f32x4 gv[2][2], bv[2][2];
; #pragma unroll
;         for (int bj = 0; bj < 2; ++bj)
; #pragma unroll
;             for (int n = 0; n < 2; ++n) { gv[bj][n] = *(const f32x4*)(gp + bj * 128 + 4 * n); bv[bj][n] = bias ? *(const f32x4*)(bias + col0 + bj * 128 + 4 * n) : (f32x4){0.f, 0.f, 0.f, 0.f}; }
; #pragma unroll
;         for (int ai = 0; ai < 2; ++ai)
; #pragma unroll
;             for (int m = 0; m < 4; ++m) { bf16_t* rowp = delta + (size_t)(row0 + ai * 128 + m * 16) * D + col0;
; #pragma unroll
;                 for (int bj = 0; bj < 2; ++bj) { const f32x4 v0 = gv[bj][0] * (acc[ai][bj][m][0] + bv[bj][0]), v1 = gv[bj][1] * (acc[ai][bj][m][1] + bv[bj][1]);
;                     u32x4 w; w.x = pk2(v0[0], v0[1]); w.y = pk2(v0[2], v0[3]); w.z = pk2(v1[0], v1[1]); w.w = pk2(v1[2], v1[3]);
;                     *(u32x4*)(rowp + bj * 128) = w; } }
.LBB0_696:
	v_lshl_or_b32 v156, s24, 8, v176
	v_lshl_add_u32 v158, s22, 8, v174
	s_cmp_lt_i32 s72, 0
	v_ashrrev_i32_e32 v157, 31, v156
	s_mov_b64 s[24:25], -1
	s_cbranch_scc0 .LBB0_698
	s_ashr_i32 s11, s22, 4
	s_mul_i32 s24, s11, 6
	s_ashr_i32 s25, s24, 31
	s_lshl_b64 s[24:25], s[24:25], 11
	s_cmp_lt_i32 s22, 64
	s_cselect_b32 s25, s25, 0
	s_cselect_b32 s24, s24, 0xc000
	s_lshl_b64 s[24:25], s[24:25], 2
	s_add_u32 s24, s48, s24
	s_addc_u32 s25, s49, s25
	v_lshl_add_u64 v[134:135], v[156:157], 2, s[24:25]
	global_load_dwordx4 v[138:141], v[134:135], off offset:16
	global_load_dwordx4 v[142:145], v[134:135], off
	global_load_dwordx4 v[130:133], v[134:135], off offset:528
	s_nop 0
	global_load_dwordx4 v[134:137], v[134:135], off offset:512
	v_and_b32_e32 v157, 15, v194
	v_bfe_u32 v170, v194, 6, 2
	v_bfe_u32 v171, v194, 4, 2
	v_bfe_u32 v172, v194, 8, 1
	v_lshlrev_b32_e32 v172, 4, v172
	v_add_u32_e32 v172, v172, v157
	v_mul_u32_u24_e32 v190, 0x110, v172
	v_lshl_add_u32 v190, v170, 6, v190
	v_lshl_add_u32 v190, v171, 4, v190
	v_add_u32_e32 v190, 0x23410, v190
	v_lshrrev_b32_e32 v172, 6, v194
	v_lshl_add_u32 v172, v172, 2, v171
	v_mul_u32_u24_e32 v191, 0x110, v172
	v_lshl_add_u32 v191, v157, 4, v191
	v_add_u32_e32 v191, 0x23410, v191
	v_sub_u32_e32 v172, v158, v157
	v_lshl_add_u32 v172, v170, 2, v172
	v_add_u32_e32 v172, v172, v171
	v_lshlrev_b32_e32 v172, 12, v172
	v_and_b32_e32 v173, 0xffffff00, v156
	v_lshlrev_b32_e32 v173, 1, v173
	v_lshl_add_u32 v173, v157, 4, v173
	v_add_u32_e32 v172, v172, v173
	v_mov_b32_e32 v173, 0
	v_lshl_add_u64 v[204:205], s[2:3], 0, v[172:173]
	s_mov_b32 s25, 0
	s_waitcnt vmcnt(0)
	v_pk_add_f32 v[126:127], v[126:127], 0 op_sel_hi:[1,0]
	v_pk_add_f32 v[128:129], v[128:129], 0 op_sel_hi:[1,0]
	v_pk_mul_f32 v[126:127], v[126:127], v[142:143]
	v_pk_mul_f32 v[128:129], v[128:129], v[144:145]
	v_pk_add_f32 v[122:123], v[122:123], 0 op_sel_hi:[1,0]
	v_pk_add_f32 v[124:125], v[124:125], 0 op_sel_hi:[1,0]
	v_pk_mul_f32 v[122:123], v[122:123], v[138:139]
	v_pk_mul_f32 v[124:125], v[124:125], v[140:141]
	v_cvt_pk_bf16_f32 v178, v126, v127
	v_cvt_pk_bf16_f32 v179, v128, v129
	v_cvt_pk_bf16_f32 v180, v122, v123
	v_cvt_pk_bf16_f32 v181, v124, v125
	ds_write_b128 v190, v[178:181]
	s_waitcnt lgkmcnt(0)
	s_barrier
	ds_read_b128 v[182:185], v191
	s_mov_b32 s24, 0x0
	v_lshl_add_u64 v[206:207], v[204:205], 0, s[24:25]
	v_pk_add_f32 v[118:119], v[118:119], 0 op_sel_hi:[1,0]
	v_pk_add_f32 v[120:121], v[120:121], 0 op_sel_hi:[1,0]
	v_pk_mul_f32 v[118:119], v[118:119], v[134:135]
	v_pk_mul_f32 v[120:121], v[120:121], v[136:137]
	v_pk_add_f32 v[114:115], v[114:115], 0 op_sel_hi:[1,0]
	v_pk_add_f32 v[116:117], v[116:117], 0 op_sel_hi:[1,0]
	v_pk_mul_f32 v[114:115], v[114:115], v[130:131]
	v_pk_mul_f32 v[116:117], v[116:117], v[132:133]
	v_cvt_pk_bf16_f32 v178, v118, v119
	v_cvt_pk_bf16_f32 v179, v120, v121
	v_cvt_pk_bf16_f32 v180, v114, v115
	v_cvt_pk_bf16_f32 v181, v116, v117
	ds_write_b128 v190, v[178:181] offset:8704
	s_waitcnt lgkmcnt(1)
	global_store_dwordx4 v[206:207], v[182:185], off
	s_waitcnt lgkmcnt(0)
	s_barrier
	ds_read_b128 v[186:189], v191 offset:8704
	v_pk_add_f32 v[110:111], v[110:111], 0 op_sel_hi:[1,0]
	v_pk_add_f32 v[112:113], v[112:113], 0 op_sel_hi:[1,0]
	v_pk_mul_f32 v[110:111], v[110:111], v[142:143]
	v_pk_mul_f32 v[112:113], v[112:113], v[144:145]
	v_pk_add_f32 v[106:107], v[106:107], 0 op_sel_hi:[1,0]
	v_pk_add_f32 v[108:109], v[108:109], 0 op_sel_hi:[1,0]
	v_pk_mul_f32 v[106:107], v[106:107], v[138:139]
	v_pk_mul_f32 v[108:109], v[108:109], v[140:141]
	v_cvt_pk_bf16_f32 v178, v110, v111
	v_cvt_pk_bf16_f32 v179, v112, v113
	v_cvt_pk_bf16_f32 v180, v106, v107
	v_cvt_pk_bf16_f32 v181, v108, v109
	ds_write_b128 v190, v[178:181]
	s_waitcnt lgkmcnt(1)
	global_store_dwordx4 v[206:207], v[186:189], off offset:256
	s_waitcnt lgkmcnt(0)
	s_barrier
	ds_read_b128 v[182:185], v191
	s_mov_b32 s24, 0x10000
	v_lshl_add_u64 v[206:207], v[204:205], 0, s[24:25]
	v_pk_add_f32 v[102:103], v[102:103], 0 op_sel_hi:[1,0]
	v_pk_add_f32 v[104:105], v[104:105], 0 op_sel_hi:[1,0]
	v_pk_mul_f32 v[102:103], v[102:103], v[134:135]
	v_pk_mul_f32 v[104:105], v[104:105], v[136:137]
	v_pk_add_f32 v[98:99], v[98:99], 0 op_sel_hi:[1,0]
	v_pk_add_f32 v[100:101], v[100:101], 0 op_sel_hi:[1,0]
	v_pk_mul_f32 v[98:99], v[98:99], v[130:131]
	v_pk_mul_f32 v[100:101], v[100:101], v[132:133]
	v_cvt_pk_bf16_f32 v178, v102, v103
	v_cvt_pk_bf16_f32 v179, v104, v105
	v_cvt_pk_bf16_f32 v180, v98, v99
	v_cvt_pk_bf16_f32 v181, v100, v101
	ds_write_b128 v190, v[178:181] offset:8704
	s_waitcnt lgkmcnt(1)
	global_store_dwordx4 v[206:207], v[182:185], off
	s_waitcnt lgkmcnt(0)
	s_barrier
	ds_read_b128 v[186:189], v191 offset:8704
	v_pk_add_f32 v[94:95], v[94:95], 0 op_sel_hi:[1,0]
	v_pk_add_f32 v[96:97], v[96:97], 0 op_sel_hi:[1,0]
	v_pk_mul_f32 v[94:95], v[94:95], v[142:143]
	v_pk_mul_f32 v[96:97], v[96:97], v[144:145]
	v_pk_add_f32 v[90:91], v[90:91], 0 op_sel_hi:[1,0]
	v_pk_add_f32 v[92:93], v[92:93], 0 op_sel_hi:[1,0]
	v_pk_mul_f32 v[90:91], v[90:91], v[138:139]
	v_pk_mul_f32 v[92:93], v[92:93], v[140:141]
	v_cvt_pk_bf16_f32 v178, v94, v95
	v_cvt_pk_bf16_f32 v179, v96, v97
	v_cvt_pk_bf16_f32 v180, v90, v91
	v_cvt_pk_bf16_f32 v181, v92, v93
	ds_write_b128 v190, v[178:181]
	s_waitcnt lgkmcnt(1)
	global_store_dwordx4 v[206:207], v[186:189], off offset:256
	s_waitcnt lgkmcnt(0)
	s_barrier
; __device__ __forceinline__ unsigned pk2(float lo, float hi) { const v2f_t f = {lo, hi}; const v2bf_t b = __builtin_convertvector(f, v2bf_t); return __builtin_bit_cast(unsigned, b); }
;     __device__ __forceinline__ void operator()(const f32x4 (&acc)[2][2][4][2], const Unit& u, int wr, int wc, int fr, int fq) const {
;     ...
;         for (int ai = 0; ai < 2; ++ai)
; #pragma unroll
;             for (int m = 0; m < 4; ++m) { bf16_t* rowp = delta + (size_t)(row0 + ai * 128 + m * 16) * D + col0;
; #pragma unroll
;                 for (int bj = 0; bj < 2; ++bj) { const f32x4 v0 = gv[bj][0] * (acc[ai][bj][m][0] + bv[bj][0]), v1 = gv[bj][1] * (acc[ai][bj][m][1] + bv[bj][1]);
;                     u32x4 w; w.x = pk2(v0[0], v0[1]); w.y = pk2(v0[2], v0[3]); w.z = pk2(v1[0], v1[1]); w.w = pk2(v1[2], v1[3]);
;                     *(u32x4*)(rowp + bj * 128) = w; } }
	ds_read_b128 v[182:185], v191
	s_mov_b32 s24, 0x20000
	v_lshl_add_u64 v[206:207], v[204:205], 0, s[24:25]
	v_pk_add_f32 v[86:87], v[86:87], 0 op_sel_hi:[1,0]
	v_pk_add_f32 v[88:89], v[88:89], 0 op_sel_hi:[1,0]
	v_pk_mul_f32 v[86:87], v[86:87], v[134:135]
	v_pk_mul_f32 v[88:89], v[88:89], v[136:137]
	v_pk_add_f32 v[82:83], v[82:83], 0 op_sel_hi:[1,0]
	v_pk_add_f32 v[84:85], v[84:85], 0 op_sel_hi:[1,0]
	v_pk_mul_f32 v[82:83], v[82:83], v[130:131]
	v_pk_mul_f32 v[84:85], v[84:85], v[132:133]
	v_cvt_pk_bf16_f32 v178, v86, v87
	v_cvt_pk_bf16_f32 v179, v88, v89
	v_cvt_pk_bf16_f32 v180, v82, v83
	v_cvt_pk_bf16_f32 v181, v84, v85
	ds_write_b128 v190, v[178:181] offset:8704
	s_waitcnt lgkmcnt(1)
	global_store_dwordx4 v[206:207], v[182:185], off
	s_waitcnt lgkmcnt(0)
	s_barrier
	ds_read_b128 v[186:189], v191 offset:8704
	v_pk_add_f32 v[78:79], v[78:79], 0 op_sel_hi:[1,0]
	v_pk_add_f32 v[80:81], v[80:81], 0 op_sel_hi:[1,0]
	v_pk_mul_f32 v[78:79], v[78:79], v[142:143]
	v_pk_mul_f32 v[80:81], v[80:81], v[144:145]
	v_pk_add_f32 v[74:75], v[74:75], 0 op_sel_hi:[1,0]
	v_pk_add_f32 v[76:77], v[76:77], 0 op_sel_hi:[1,0]
	v_pk_mul_f32 v[74:75], v[74:75], v[138:139]
	v_pk_mul_f32 v[76:77], v[76:77], v[140:141]
	v_cvt_pk_bf16_f32 v178, v78, v79
	v_cvt_pk_bf16_f32 v179, v80, v81
	v_cvt_pk_bf16_f32 v180, v74, v75
	v_cvt_pk_bf16_f32 v181, v76, v77
	ds_write_b128 v190, v[178:181]
	s_waitcnt lgkmcnt(1)
	global_store_dwordx4 v[206:207], v[186:189], off offset:256
	s_waitcnt lgkmcnt(0)
	s_barrier
	ds_read_b128 v[182:185], v191
	s_mov_b32 s24, 0x30000
	v_lshl_add_u64 v[206:207], v[204:205], 0, s[24:25]
	v_pk_add_f32 v[70:71], v[70:71], 0 op_sel_hi:[1,0]
	v_pk_add_f32 v[72:73], v[72:73], 0 op_sel_hi:[1,0]
	v_pk_mul_f32 v[70:71], v[70:71], v[134:135]
	v_pk_mul_f32 v[72:73], v[72:73], v[136:137]
	v_pk_add_f32 v[66:67], v[66:67], 0 op_sel_hi:[1,0]
	v_pk_add_f32 v[68:69], v[68:69], 0 op_sel_hi:[1,0]
	v_pk_mul_f32 v[66:67], v[66:67], v[130:131]
	v_pk_mul_f32 v[68:69], v[68:69], v[132:133]
	v_cvt_pk_bf16_f32 v178, v70, v71
	v_cvt_pk_bf16_f32 v179, v72, v73
	v_cvt_pk_bf16_f32 v180, v66, v67
	v_cvt_pk_bf16_f32 v181, v68, v69
	ds_write_b128 v190, v[178:181] offset:8704
	s_waitcnt lgkmcnt(1)
	global_store_dwordx4 v[206:207], v[182:185], off
	s_waitcnt lgkmcnt(0)
	s_barrier
	ds_read_b128 v[186:189], v191 offset:8704
	v_pk_add_f32 v[60:61], v[60:61], 0 op_sel_hi:[1,0]
	v_pk_add_f32 v[62:63], v[62:63], 0 op_sel_hi:[1,0]
	v_pk_mul_f32 v[60:61], v[60:61], v[142:143]
	v_pk_mul_f32 v[62:63], v[62:63], v[144:145]
	v_pk_add_f32 v[56:57], v[56:57], 0 op_sel_hi:[1,0]
	v_pk_add_f32 v[58:59], v[58:59], 0 op_sel_hi:[1,0]
	v_pk_mul_f32 v[56:57], v[56:57], v[138:139]
	v_pk_mul_f32 v[58:59], v[58:59], v[140:141]
	v_cvt_pk_bf16_f32 v178, v60, v61
	v_cvt_pk_bf16_f32 v179, v62, v63
	v_cvt_pk_bf16_f32 v180, v56, v57
	v_cvt_pk_bf16_f32 v181, v58, v59
	ds_write_b128 v190, v[178:181]
	s_waitcnt lgkmcnt(1)
	global_store_dwordx4 v[206:207], v[186:189], off offset:256
	s_waitcnt lgkmcnt(0)
	s_barrier
	ds_read_b128 v[182:185], v191
	s_mov_b32 s24, 0x80000
	v_lshl_add_u64 v[206:207], v[204:205], 0, s[24:25]
	v_pk_add_f32 v[52:53], v[52:53], 0 op_sel_hi:[1,0]
	v_pk_add_f32 v[54:55], v[54:55], 0 op_sel_hi:[1,0]
	v_pk_mul_f32 v[52:53], v[52:53], v[134:135]
	v_pk_mul_f32 v[54:55], v[54:55], v[136:137]
	v_pk_add_f32 v[48:49], v[48:49], 0 op_sel_hi:[1,0]
	v_pk_add_f32 v[50:51], v[50:51], 0 op_sel_hi:[1,0]
	v_pk_mul_f32 v[48:49], v[48:49], v[130:131]
	v_pk_mul_f32 v[50:51], v[50:51], v[132:133]
	v_cvt_pk_bf16_f32 v178, v52, v53
	v_cvt_pk_bf16_f32 v179, v54, v55
	v_cvt_pk_bf16_f32 v180, v48, v49
	v_cvt_pk_bf16_f32 v181, v50, v51
	ds_write_b128 v190, v[178:181] offset:8704
	s_waitcnt lgkmcnt(1)
	global_store_dwordx4 v[206:207], v[182:185], off
	s_waitcnt lgkmcnt(0)
	s_barrier
	ds_read_b128 v[186:189], v191 offset:8704
	v_pk_add_f32 v[44:45], v[44:45], 0 op_sel_hi:[1,0]
	v_pk_add_f32 v[46:47], v[46:47], 0 op_sel_hi:[1,0]
	v_pk_mul_f32 v[44:45], v[44:45], v[142:143]
	v_pk_mul_f32 v[46:47], v[46:47], v[144:145]
	v_pk_add_f32 v[40:41], v[40:41], 0 op_sel_hi:[1,0]
	v_pk_add_f32 v[42:43], v[42:43], 0 op_sel_hi:[1,0]
	v_pk_mul_f32 v[40:41], v[40:41], v[138:139]
	v_pk_mul_f32 v[42:43], v[42:43], v[140:141]
	v_cvt_pk_bf16_f32 v178, v44, v45
	v_cvt_pk_bf16_f32 v179, v46, v47
	v_cvt_pk_bf16_f32 v180, v40, v41
	v_cvt_pk_bf16_f32 v181, v42, v43
	ds_write_b128 v190, v[178:181]
	s_waitcnt lgkmcnt(1)
	global_store_dwordx4 v[206:207], v[186:189], off offset:256
	s_waitcnt lgkmcnt(0)
	s_barrier
; __device__ __forceinline__ unsigned pk2(float lo, float hi) { const v2f_t f = {lo, hi}; const v2bf_t b = __builtin_convertvector(f, v2bf_t); return __builtin_bit_cast(unsigned, b); }
;     __device__ __forceinline__ void operator()(const f32x4 (&acc)[2][2][4][2], const Unit& u, int wr, int wc, int fr, int fq) const {
;     ...
;         for (int ai = 0; ai < 2; ++ai)
; #pragma unroll
;             for (int m = 0; m < 4; ++m) { bf16_t* rowp = delta + (size_t)(row0 + ai * 128 + m * 16) * D + col0;
; #pragma unroll
;                 for (int bj = 0; bj < 2; ++bj) { const f32x4 v0 = gv[bj][0] * (acc[ai][bj][m][0] + bv[bj][0]), v1 = gv[bj][1] * (acc[ai][bj][m][1] + bv[bj][1]);
;                     u32x4 w; w.x = pk2(v0[0], v0[1]); w.y = pk2(v0[2], v0[3]); w.z = pk2(v1[0], v1[1]); w.w = pk2(v1[2], v1[3]);
;                     *(u32x4*)(rowp + bj * 128) = w; } }
	ds_read_b128 v[182:185], v191
	s_mov_b32 s24, 0x90000
	v_lshl_add_u64 v[206:207], v[204:205], 0, s[24:25]
	v_pk_add_f32 v[36:37], v[36:37], 0 op_sel_hi:[1,0]
	v_pk_add_f32 v[38:39], v[38:39], 0 op_sel_hi:[1,0]
	v_pk_mul_f32 v[36:37], v[36:37], v[134:135]
	v_pk_mul_f32 v[38:39], v[38:39], v[136:137]
	v_pk_add_f32 v[32:33], v[32:33], 0 op_sel_hi:[1,0]
	v_pk_add_f32 v[34:35], v[34:35], 0 op_sel_hi:[1,0]
	v_pk_mul_f32 v[32:33], v[32:33], v[130:131]
	v_pk_mul_f32 v[34:35], v[34:35], v[132:133]
	v_cvt_pk_bf16_f32 v178, v36, v37
	v_cvt_pk_bf16_f32 v179, v38, v39
	v_cvt_pk_bf16_f32 v180, v32, v33
	v_cvt_pk_bf16_f32 v181, v34, v35
	ds_write_b128 v190, v[178:181] offset:8704
	s_waitcnt lgkmcnt(1)
	global_store_dwordx4 v[206:207], v[182:185], off
	s_waitcnt lgkmcnt(0)
	s_barrier
	ds_read_b128 v[186:189], v191 offset:8704
	v_pk_add_f32 v[28:29], v[28:29], 0 op_sel_hi:[1,0]
	v_pk_add_f32 v[30:31], v[30:31], 0 op_sel_hi:[1,0]
	v_pk_mul_f32 v[28:29], v[28:29], v[142:143]
	v_pk_mul_f32 v[30:31], v[30:31], v[144:145]
	v_pk_add_f32 v[24:25], v[24:25], 0 op_sel_hi:[1,0]
	v_pk_add_f32 v[26:27], v[26:27], 0 op_sel_hi:[1,0]
	v_pk_mul_f32 v[24:25], v[24:25], v[138:139]
	v_pk_mul_f32 v[26:27], v[26:27], v[140:141]
	v_cvt_pk_bf16_f32 v178, v28, v29
	v_cvt_pk_bf16_f32 v179, v30, v31
	v_cvt_pk_bf16_f32 v180, v24, v25
	v_cvt_pk_bf16_f32 v181, v26, v27
	ds_write_b128 v190, v[178:181]
	s_waitcnt lgkmcnt(1)
	global_store_dwordx4 v[206:207], v[186:189], off offset:256
	s_waitcnt lgkmcnt(0)
	s_barrier
	ds_read_b128 v[182:185], v191
	s_mov_b32 s24, 0xa0000
	v_lshl_add_u64 v[206:207], v[204:205], 0, s[24:25]
	v_pk_add_f32 v[20:21], v[20:21], 0 op_sel_hi:[1,0]
	v_pk_add_f32 v[22:23], v[22:23], 0 op_sel_hi:[1,0]
	v_pk_mul_f32 v[20:21], v[20:21], v[134:135]
	v_pk_mul_f32 v[22:23], v[22:23], v[136:137]
	v_pk_add_f32 v[16:17], v[16:17], 0 op_sel_hi:[1,0]
	v_pk_add_f32 v[18:19], v[18:19], 0 op_sel_hi:[1,0]
	v_pk_mul_f32 v[16:17], v[16:17], v[130:131]
	v_pk_mul_f32 v[18:19], v[18:19], v[132:133]
	v_cvt_pk_bf16_f32 v178, v20, v21
	v_cvt_pk_bf16_f32 v179, v22, v23
	v_cvt_pk_bf16_f32 v180, v16, v17
	v_cvt_pk_bf16_f32 v181, v18, v19
	ds_write_b128 v190, v[178:181] offset:8704
	s_waitcnt lgkmcnt(1)
	global_store_dwordx4 v[206:207], v[182:185], off
	s_waitcnt lgkmcnt(0)
	s_barrier
	ds_read_b128 v[186:189], v191 offset:8704
	v_pk_add_f32 v[12:13], v[12:13], 0 op_sel_hi:[1,0]
	v_pk_add_f32 v[14:15], v[14:15], 0 op_sel_hi:[1,0]
	v_pk_mul_f32 v[12:13], v[12:13], v[142:143]
	v_pk_mul_f32 v[14:15], v[14:15], v[144:145]
	v_pk_add_f32 v[8:9], v[8:9], 0 op_sel_hi:[1,0]
	v_pk_add_f32 v[10:11], v[10:11], 0 op_sel_hi:[1,0]
	v_pk_mul_f32 v[8:9], v[8:9], v[138:139]
	v_pk_mul_f32 v[10:11], v[10:11], v[140:141]
	v_cvt_pk_bf16_f32 v178, v12, v13
	v_cvt_pk_bf16_f32 v179, v14, v15
	v_cvt_pk_bf16_f32 v180, v8, v9
	v_cvt_pk_bf16_f32 v181, v10, v11
	ds_write_b128 v190, v[178:181]
	s_waitcnt lgkmcnt(1)
	global_store_dwordx4 v[206:207], v[186:189], off offset:256
	s_waitcnt lgkmcnt(0)
	s_barrier
	ds_read_b128 v[182:185], v191
	s_mov_b32 s24, 0xb0000
	v_lshl_add_u64 v[206:207], v[204:205], 0, s[24:25]
	v_pk_add_f32 v[4:5], v[4:5], 0 op_sel_hi:[1,0]
	v_pk_add_f32 v[6:7], v[6:7], 0 op_sel_hi:[1,0]
	v_pk_mul_f32 v[4:5], v[4:5], v[134:135]
	v_pk_mul_f32 v[6:7], v[6:7], v[136:137]
	v_pk_add_f32 v[0:1], v[0:1], 0 op_sel_hi:[1,0]
	v_pk_add_f32 v[2:3], v[2:3], 0 op_sel_hi:[1,0]
	v_pk_mul_f32 v[0:1], v[0:1], v[130:131]
	v_pk_mul_f32 v[2:3], v[2:3], v[132:133]
	v_cvt_pk_bf16_f32 v178, v4, v5
	v_cvt_pk_bf16_f32 v179, v6, v7
	v_cvt_pk_bf16_f32 v180, v0, v1
	v_cvt_pk_bf16_f32 v181, v2, v3
	ds_write_b128 v190, v[178:181] offset:8704
	s_waitcnt lgkmcnt(1)
	global_store_dwordx4 v[206:207], v[182:185], off
	s_waitcnt lgkmcnt(0)
	s_barrier
	ds_read_b128 v[186:189], v191 offset:8704
	s_waitcnt lgkmcnt(0)
	global_store_dwordx4 v[206:207], v[186:189], off offset:256
	s_mov_b64 s[24:25], 0

; __device__ __forceinline__ unsigned pk2(float lo, float hi) { const v2f_t f = {lo, hi}; const v2bf_t b = __builtin_convertvector(f, v2bf_t); return __builtin_bit_cast(unsigned, b); }
;     __device__ __forceinline__ void operator()(const f32x4 (&acc)[2][2][4][2], const Unit& u, int wr, int wc, int fr, int fq) const {
;         const int row0 = u.pm * 256 + wr * 64 + fr, col0 = u.pn * 256 + wc * 32 + 8 * fq;
;         f32x4 bv[2][2];
; #pragma unroll
;         for (int bj = 0; bj < 2; ++bj)
; #pragma unroll
;             for (int n = 0; n < 2; ++n) bv[bj][n] = *(const f32x4*)(bias + col0 + bj * 128 + 4 * n);
; #pragma unroll
;         for (int ai = 0; ai < 2; ++ai)
; #pragma unroll
;             for (int m = 0; m < 4; ++m) { bf16_t* rowp = a1 + (size_t)(row0 + ai * 128 + m * 16) * DFF + col0;
; #pragma unroll
;                 for (int bj = 0; bj < 2; ++bj) { f32x4 v0 = acc[ai][bj][m][0] + bv[bj][0], v1 = acc[ai][bj][m][1] + bv[bj][1];
; #pragma unroll
;                     for (int j = 0; j < 4; ++j) { const float a = fmaxf(v0[j], 0.f), b = fmaxf(v1[j], 0.f); v0[j] = a * a; v1[j] = b * b; }
;                     u32x4 w; w.x = pk2(v0[0], v0[1]); w.y = pk2(v0[2], v0[3]); w.z = pk2(v1[0], v1[1]); w.w = pk2(v1[2], v1[3]);
;                     *(u32x4*)(rowp + bj * 128) = w; } }
.LBB0_851:
	v_lshl_or_b32 v156, s34, 8, v172
	v_ashrrev_i32_e32 v157, 31, v156
	v_lshl_add_u64 v[118:119], v[156:157], 2, s[18:19]
	global_load_dwordx4 v[122:125], v[118:119], off offset:16
	global_load_dwordx4 v[126:129], v[118:119], off
	global_load_dwordx4 v[114:117], v[118:119], off offset:528
	s_nop 0
	global_load_dwordx4 v[118:121], v[118:119], off offset:512
	v_bfe_u32 v156, v194, 8, 1
	v_lshlrev_b32_e32 v156, 4, v156
	v_and_b32_e32 v157, 15, v194
	v_add_u32_e32 v156, v156, v157
	v_mul_u32_u24_e32 v186, 0x110, v156
	v_bfe_u32 v158, v194, 6, 2
	v_bfe_u32 v159, v194, 4, 2
	v_lshl_add_u32 v186, v158, 6, v186
	v_lshl_add_u32 v186, v159, 4, v186
	v_add_u32_e32 v186, 0x23410, v186
	v_lshrrev_b32_e32 v160, 6, v194
	v_lshl_add_u32 v160, v160, 2, v159
	v_mul_u32_u24_e32 v187, 0x110, v160
	v_lshl_add_u32 v187, v157, 4, v187
	v_add_u32_e32 v187, 0x23410, v187
	v_bfe_u32 v156, v194, 8, 1
	v_lshlrev_b32_e32 v156, 6, v156
	v_lshl_add_u32 v156, v158, 2, v156
	v_add_u32_e32 v156, v156, v159
	v_lshl_add_u32 v160, s30, 8, v156
	v_mov_b32_e32 v161, 0
	v_lshlrev_b64 v[160:161], 14, v[160:161]
	v_lshlrev_b32_e32 v158, 4, v157
	v_lshl_add_u32 v158, s34, 9, v158
	v_mov_b32_e32 v159, 0
	v_lshl_add_u64 v[188:189], s[14:15], 0, v[160:161]
	v_lshl_add_u64 v[188:189], v[188:189], 0, v[158:159]
	s_mov_b32 s21, 0x200000
	s_mov_b64 s[36:37], 0x200000
	s_mov_b32 s62, s61
	s_mov_b32 s34, s20
	s_mov_b32 s30, s22
	s_mov_b64 s[38:39], s[28:29]
	s_mov_b32 s99, 0
	s_waitcnt vmcnt(0)
	v_pk_add_f32 v[142:143], v[142:143], v[126:127]
	v_pk_add_f32 v[144:145], v[144:145], v[128:129]
	v_max_f32_e32 v142, 0, v142
	v_max_f32_e32 v143, 0, v143
	v_max_f32_e32 v144, 0, v144
	v_max_f32_e32 v145, 0, v145
	v_pk_mul_f32 v[142:143], v[142:143], v[142:143]
	v_pk_mul_f32 v[144:145], v[144:145], v[144:145]
	v_pk_add_f32 v[138:139], v[138:139], v[122:123]
	v_pk_add_f32 v[140:141], v[140:141], v[124:125]
	v_max_f32_e32 v138, 0, v138
	v_max_f32_e32 v139, 0, v139
	v_max_f32_e32 v140, 0, v140
	v_max_f32_e32 v141, 0, v141
	v_pk_mul_f32 v[138:139], v[138:139], v[138:139]
	v_pk_mul_f32 v[140:141], v[140:141], v[140:141]
	v_cvt_pk_bf16_f32 v174, v142, v143
	v_cvt_pk_bf16_f32 v175, v144, v145
	v_cvt_pk_bf16_f32 v176, v138, v139
	v_cvt_pk_bf16_f32 v177, v140, v141
	ds_write_b128 v186, v[174:177]
	s_waitcnt lgkmcnt(0)
	s_barrier
	ds_read_b128 v[178:181], v187
	s_mov_b32 s98, 0x0
	v_lshl_add_u64 v[190:191], v[188:189], 0, s[98:99]
	v_pk_add_f32 v[134:135], v[134:135], v[118:119]
	v_pk_add_f32 v[136:137], v[136:137], v[120:121]
	v_max_f32_e32 v134, 0, v134
	v_max_f32_e32 v135, 0, v135
	v_max_f32_e32 v136, 0, v136
	v_max_f32_e32 v137, 0, v137
	v_pk_mul_f32 v[134:135], v[134:135], v[134:135]
	v_pk_mul_f32 v[136:137], v[136:137], v[136:137]
	v_pk_add_f32 v[130:131], v[130:131], v[114:115]
	v_pk_add_f32 v[132:133], v[132:133], v[116:117]
	v_max_f32_e32 v130, 0, v130
	v_max_f32_e32 v131, 0, v131
	v_max_f32_e32 v132, 0, v132
	v_max_f32_e32 v133, 0, v133
	v_pk_mul_f32 v[130:131], v[130:131], v[130:131]
	v_pk_mul_f32 v[132:133], v[132:133], v[132:133]
	v_cvt_pk_bf16_f32 v174, v134, v135
	v_cvt_pk_bf16_f32 v175, v136, v137
	v_cvt_pk_bf16_f32 v176, v130, v131
	v_cvt_pk_bf16_f32 v177, v132, v133
	ds_write_b128 v186, v[174:177] offset:8704
	s_waitcnt lgkmcnt(1)
	global_store_dwordx4 v[190:191], v[178:181], off
	s_waitcnt lgkmcnt(0)
	s_barrier
	ds_read_b128 v[182:185], v187 offset:8704
	v_pk_add_f32 v[110:111], v[110:111], v[126:127]
	v_pk_add_f32 v[112:113], v[112:113], v[128:129]
	v_max_f32_e32 v110, 0, v110
	v_max_f32_e32 v111, 0, v111
	v_max_f32_e32 v112, 0, v112
	v_max_f32_e32 v113, 0, v113
	v_pk_mul_f32 v[110:111], v[110:111], v[110:111]
	v_pk_mul_f32 v[112:113], v[112:113], v[112:113]
	v_pk_add_f32 v[106:107], v[106:107], v[122:123]
	v_pk_add_f32 v[108:109], v[108:109], v[124:125]
	v_max_f32_e32 v106, 0, v106
	v_max_f32_e32 v107, 0, v107
	v_max_f32_e32 v108, 0, v108
	v_max_f32_e32 v109, 0, v109
	v_pk_mul_f32 v[106:107], v[106:107], v[106:107]
	v_pk_mul_f32 v[108:109], v[108:109], v[108:109]
	v_cvt_pk_bf16_f32 v174, v110, v111
	v_cvt_pk_bf16_f32 v175, v112, v113
	v_cvt_pk_bf16_f32 v176, v106, v107
	v_cvt_pk_bf16_f32 v177, v108, v109
	ds_write_b128 v186, v[174:177]
	s_waitcnt lgkmcnt(1)
	global_store_dwordx4 v[190:191], v[182:185], off offset:256
	s_waitcnt lgkmcnt(0)
	s_barrier
	ds_read_b128 v[178:181], v187
	s_mov_b32 s98, 0x40000
	v_lshl_add_u64 v[190:191], v[188:189], 0, s[98:99]
	v_pk_add_f32 v[102:103], v[102:103], v[118:119]
	v_pk_add_f32 v[104:105], v[104:105], v[120:121]
	v_max_f32_e32 v102, 0, v102
	v_max_f32_e32 v103, 0, v103
	v_max_f32_e32 v104, 0, v104
	v_max_f32_e32 v105, 0, v105
	v_pk_mul_f32 v[102:103], v[102:103], v[102:103]
	v_pk_mul_f32 v[104:105], v[104:105], v[104:105]
	v_pk_add_f32 v[98:99], v[98:99], v[114:115]
	v_pk_add_f32 v[100:101], v[100:101], v[116:117]
	v_max_f32_e32 v98, 0, v98
	v_max_f32_e32 v99, 0, v99
	v_max_f32_e32 v100, 0, v100
	v_max_f32_e32 v101, 0, v101
	v_pk_mul_f32 v[98:99], v[98:99], v[98:99]
	v_pk_mul_f32 v[100:101], v[100:101], v[100:101]
	v_cvt_pk_bf16_f32 v174, v102, v103
	v_cvt_pk_bf16_f32 v175, v104, v105
	v_cvt_pk_bf16_f32 v176, v98, v99
	v_cvt_pk_bf16_f32 v177, v100, v101
	ds_write_b128 v186, v[174:177] offset:8704
	s_waitcnt lgkmcnt(1)
	global_store_dwordx4 v[190:191], v[178:181], off
	s_waitcnt lgkmcnt(0)
	s_barrier
; __device__ __forceinline__ unsigned pk2(float lo, float hi) { const v2f_t f = {lo, hi}; const v2bf_t b = __builtin_convertvector(f, v2bf_t); return __builtin_bit_cast(unsigned, b); }
;     __device__ __forceinline__ void operator()(const f32x4 (&acc)[2][2][4][2], const Unit& u, int wr, int wc, int fr, int fq) const {
;     ...
;         for (int ai = 0; ai < 2; ++ai)
; #pragma unroll
;             for (int m = 0; m < 4; ++m) { bf16_t* rowp = a1 + (size_t)(row0 + ai * 128 + m * 16) * DFF + col0;
; #pragma unroll
;                 for (int bj = 0; bj < 2; ++bj) { f32x4 v0 = acc[ai][bj][m][0] + bv[bj][0], v1 = acc[ai][bj][m][1] + bv[bj][1];
; #pragma unroll
;                     for (int j = 0; j < 4; ++j) { const float a = fmaxf(v0[j], 0.f), b = fmaxf(v1[j], 0.f); v0[j] = a * a; v1[j] = b * b; }
;                     u32x4 w; w.x = pk2(v0[0], v0[1]); w.y = pk2(v0[2], v0[3]); w.z = pk2(v1[0], v1[1]); w.w = pk2(v1[2], v1[3]);
;                     *(u32x4*)(rowp + bj * 128) = w; } }
	ds_read_b128 v[182:185], v187 offset:8704
	v_pk_add_f32 v[94:95], v[94:95], v[126:127]
	v_pk_add_f32 v[96:97], v[96:97], v[128:129]
	v_max_f32_e32 v94, 0, v94
	v_max_f32_e32 v95, 0, v95
	v_max_f32_e32 v96, 0, v96
	v_max_f32_e32 v97, 0, v97
	v_pk_mul_f32 v[94:95], v[94:95], v[94:95]
	v_pk_mul_f32 v[96:97], v[96:97], v[96:97]
	v_pk_add_f32 v[90:91], v[90:91], v[122:123]
	v_pk_add_f32 v[92:93], v[92:93], v[124:125]
	v_max_f32_e32 v90, 0, v90
	v_max_f32_e32 v91, 0, v91
	v_max_f32_e32 v92, 0, v92
	v_max_f32_e32 v93, 0, v93
	v_pk_mul_f32 v[90:91], v[90:91], v[90:91]
	v_pk_mul_f32 v[92:93], v[92:93], v[92:93]
	v_cvt_pk_bf16_f32 v174, v94, v95
	v_cvt_pk_bf16_f32 v175, v96, v97
	v_cvt_pk_bf16_f32 v176, v90, v91
	v_cvt_pk_bf16_f32 v177, v92, v93
	ds_write_b128 v186, v[174:177]
	s_waitcnt lgkmcnt(1)
	global_store_dwordx4 v[190:191], v[182:185], off offset:256
	s_waitcnt lgkmcnt(0)
	s_barrier
	ds_read_b128 v[178:181], v187
	s_mov_b32 s98, 0x80000
	v_lshl_add_u64 v[190:191], v[188:189], 0, s[98:99]
	v_pk_add_f32 v[86:87], v[86:87], v[118:119]
	v_pk_add_f32 v[88:89], v[88:89], v[120:121]
	v_max_f32_e32 v86, 0, v86
	v_max_f32_e32 v87, 0, v87
	v_max_f32_e32 v88, 0, v88
	v_max_f32_e32 v89, 0, v89
	v_pk_mul_f32 v[86:87], v[86:87], v[86:87]
	v_pk_mul_f32 v[88:89], v[88:89], v[88:89]
	v_pk_add_f32 v[82:83], v[82:83], v[114:115]
	v_pk_add_f32 v[84:85], v[84:85], v[116:117]
	v_max_f32_e32 v82, 0, v82
	v_max_f32_e32 v83, 0, v83
	v_max_f32_e32 v84, 0, v84
	v_max_f32_e32 v85, 0, v85
	v_pk_mul_f32 v[82:83], v[82:83], v[82:83]
	v_pk_mul_f32 v[84:85], v[84:85], v[84:85]
	v_cvt_pk_bf16_f32 v174, v86, v87
	v_cvt_pk_bf16_f32 v175, v88, v89
	v_cvt_pk_bf16_f32 v176, v82, v83
	v_cvt_pk_bf16_f32 v177, v84, v85
	ds_write_b128 v186, v[174:177] offset:8704
	s_waitcnt lgkmcnt(1)
	global_store_dwordx4 v[190:191], v[178:181], off
	s_waitcnt lgkmcnt(0)
	s_barrier
	ds_read_b128 v[182:185], v187 offset:8704
	v_pk_add_f32 v[78:79], v[78:79], v[126:127]
	v_pk_add_f32 v[80:81], v[80:81], v[128:129]
	v_max_f32_e32 v78, 0, v78
	v_max_f32_e32 v79, 0, v79
	v_max_f32_e32 v80, 0, v80
	v_max_f32_e32 v81, 0, v81
	v_pk_mul_f32 v[78:79], v[78:79], v[78:79]
	v_pk_mul_f32 v[80:81], v[80:81], v[80:81]
	v_pk_add_f32 v[74:75], v[74:75], v[122:123]
	v_pk_add_f32 v[76:77], v[76:77], v[124:125]
	v_max_f32_e32 v74, 0, v74
	v_max_f32_e32 v75, 0, v75
	v_max_f32_e32 v76, 0, v76
	v_max_f32_e32 v77, 0, v77
	v_pk_mul_f32 v[74:75], v[74:75], v[74:75]
	v_pk_mul_f32 v[76:77], v[76:77], v[76:77]
	v_cvt_pk_bf16_f32 v174, v78, v79
	v_cvt_pk_bf16_f32 v175, v80, v81
	v_cvt_pk_bf16_f32 v176, v74, v75
	v_cvt_pk_bf16_f32 v177, v76, v77
	ds_write_b128 v186, v[174:177]
	s_waitcnt lgkmcnt(1)
	global_store_dwordx4 v[190:191], v[182:185], off offset:256
	s_waitcnt lgkmcnt(0)
	s_barrier
	ds_read_b128 v[178:181], v187
	s_mov_b32 s98, 0xc0000
	v_lshl_add_u64 v[190:191], v[188:189], 0, s[98:99]
	v_pk_add_f32 v[70:71], v[70:71], v[118:119]
	v_pk_add_f32 v[72:73], v[72:73], v[120:121]
	v_max_f32_e32 v70, 0, v70
	v_max_f32_e32 v71, 0, v71
	v_max_f32_e32 v72, 0, v72
	v_max_f32_e32 v73, 0, v73
	v_pk_mul_f32 v[70:71], v[70:71], v[70:71]
	v_pk_mul_f32 v[72:73], v[72:73], v[72:73]
	v_pk_add_f32 v[66:67], v[66:67], v[114:115]
	v_pk_add_f32 v[68:69], v[68:69], v[116:117]
	v_max_f32_e32 v66, 0, v66
	v_max_f32_e32 v67, 0, v67
	v_max_f32_e32 v68, 0, v68
	v_max_f32_e32 v69, 0, v69
	v_pk_mul_f32 v[66:67], v[66:67], v[66:67]
	v_pk_mul_f32 v[68:69], v[68:69], v[68:69]
	v_cvt_pk_bf16_f32 v174, v70, v71
	v_cvt_pk_bf16_f32 v175, v72, v73
	v_cvt_pk_bf16_f32 v176, v66, v67
	v_cvt_pk_bf16_f32 v177, v68, v69
	ds_write_b128 v186, v[174:177] offset:8704
	s_waitcnt lgkmcnt(1)
	global_store_dwordx4 v[190:191], v[178:181], off
	s_waitcnt lgkmcnt(0)
	s_barrier
	ds_read_b128 v[182:185], v187 offset:8704
	v_pk_add_f32 v[60:61], v[60:61], v[126:127]
	v_pk_add_f32 v[62:63], v[62:63], v[128:129]
	v_max_f32_e32 v60, 0, v60
	v_max_f32_e32 v61, 0, v61
	v_max_f32_e32 v62, 0, v62
	v_max_f32_e32 v63, 0, v63
	v_pk_mul_f32 v[60:61], v[60:61], v[60:61]
	v_pk_mul_f32 v[62:63], v[62:63], v[62:63]
	v_pk_add_f32 v[56:57], v[56:57], v[122:123]
	v_pk_add_f32 v[58:59], v[58:59], v[124:125]
	v_max_f32_e32 v56, 0, v56
	v_max_f32_e32 v57, 0, v57
	v_max_f32_e32 v58, 0, v58
	v_max_f32_e32 v59, 0, v59
	v_pk_mul_f32 v[56:57], v[56:57], v[56:57]
	v_pk_mul_f32 v[58:59], v[58:59], v[58:59]
	v_cvt_pk_bf16_f32 v174, v60, v61
	v_cvt_pk_bf16_f32 v175, v62, v63
	v_cvt_pk_bf16_f32 v176, v56, v57
	v_cvt_pk_bf16_f32 v177, v58, v59
	ds_write_b128 v186, v[174:177]
	s_waitcnt lgkmcnt(1)
	global_store_dwordx4 v[190:191], v[182:185], off offset:256
	s_waitcnt lgkmcnt(0)
	s_barrier
	ds_read_b128 v[178:181], v187
	s_mov_b32 s98, 0x200000
	v_lshl_add_u64 v[190:191], v[188:189], 0, s[98:99]
	v_pk_add_f32 v[52:53], v[52:53], v[118:119]
	v_pk_add_f32 v[54:55], v[54:55], v[120:121]
	v_max_f32_e32 v52, 0, v52
	v_max_f32_e32 v53, 0, v53
	v_max_f32_e32 v54, 0, v54
	v_max_f32_e32 v55, 0, v55
	v_pk_mul_f32 v[52:53], v[52:53], v[52:53]
	v_pk_mul_f32 v[54:55], v[54:55], v[54:55]
	v_pk_add_f32 v[48:49], v[48:49], v[114:115]
	v_pk_add_f32 v[50:51], v[50:51], v[116:117]
	v_max_f32_e32 v48, 0, v48
	v_max_f32_e32 v49, 0, v49
	v_max_f32_e32 v50, 0, v50
	v_max_f32_e32 v51, 0, v51
	v_pk_mul_f32 v[48:49], v[48:49], v[48:49]
	v_pk_mul_f32 v[50:51], v[50:51], v[50:51]
	v_cvt_pk_bf16_f32 v174, v52, v53
	v_cvt_pk_bf16_f32 v175, v54, v55
	v_cvt_pk_bf16_f32 v176, v48, v49
	v_cvt_pk_bf16_f32 v177, v50, v51
	ds_write_b128 v186, v[174:177] offset:8704
	s_waitcnt lgkmcnt(1)
	global_store_dwordx4 v[190:191], v[178:181], off
	s_waitcnt lgkmcnt(0)
	s_barrier
; __device__ __forceinline__ unsigned pk2(float lo, float hi) { const v2f_t f = {lo, hi}; const v2bf_t b = __builtin_convertvector(f, v2bf_t); return __builtin_bit_cast(unsigned, b); }
;     __device__ __forceinline__ void operator()(const f32x4 (&acc)[2][2][4][2], const Unit& u, int wr, int wc, int fr, int fq) const {
;     ...
;         for (int ai = 0; ai < 2; ++ai)
; #pragma unroll
;             for (int m = 0; m < 4; ++m) { bf16_t* rowp = a1 + (size_t)(row0 + ai * 128 + m * 16) * DFF + col0;
; #pragma unroll
;                 for (int bj = 0; bj < 2; ++bj) { f32x4 v0 = acc[ai][bj][m][0] + bv[bj][0], v1 = acc[ai][bj][m][1] + bv[bj][1];
; #pragma unroll
;                     for (int j = 0; j < 4; ++j) { const float a = fmaxf(v0[j], 0.f), b = fmaxf(v1[j], 0.f); v0[j] = a * a; v1[j] = b * b; }
;                     u32x4 w; w.x = pk2(v0[0], v0[1]); w.y = pk2(v0[2], v0[3]); w.z = pk2(v1[0], v1[1]); w.w = pk2(v1[2], v1[3]);
;                     *(u32x4*)(rowp + bj * 128) = w; } }
	ds_read_b128 v[182:185], v187 offset:8704
	v_pk_add_f32 v[44:45], v[44:45], v[126:127]
	v_pk_add_f32 v[46:47], v[46:47], v[128:129]
	v_max_f32_e32 v44, 0, v44
	v_max_f32_e32 v45, 0, v45
	v_max_f32_e32 v46, 0, v46
	v_max_f32_e32 v47, 0, v47
	v_pk_mul_f32 v[44:45], v[44:45], v[44:45]
	v_pk_mul_f32 v[46:47], v[46:47], v[46:47]
	v_pk_add_f32 v[40:41], v[40:41], v[122:123]
	v_pk_add_f32 v[42:43], v[42:43], v[124:125]
	v_max_f32_e32 v40, 0, v40
	v_max_f32_e32 v41, 0, v41
	v_max_f32_e32 v42, 0, v42
	v_max_f32_e32 v43, 0, v43
	v_pk_mul_f32 v[40:41], v[40:41], v[40:41]
	v_pk_mul_f32 v[42:43], v[42:43], v[42:43]
	v_cvt_pk_bf16_f32 v174, v44, v45
	v_cvt_pk_bf16_f32 v175, v46, v47
	v_cvt_pk_bf16_f32 v176, v40, v41
	v_cvt_pk_bf16_f32 v177, v42, v43
	ds_write_b128 v186, v[174:177]
	s_waitcnt lgkmcnt(1)
	global_store_dwordx4 v[190:191], v[182:185], off offset:256
	s_waitcnt lgkmcnt(0)
	s_barrier
	ds_read_b128 v[178:181], v187
	s_mov_b32 s98, 0x240000
	v_lshl_add_u64 v[190:191], v[188:189], 0, s[98:99]
	v_pk_add_f32 v[36:37], v[36:37], v[118:119]
	v_pk_add_f32 v[38:39], v[38:39], v[120:121]
	v_max_f32_e32 v36, 0, v36
	v_max_f32_e32 v37, 0, v37
	v_max_f32_e32 v38, 0, v38
	v_max_f32_e32 v39, 0, v39
	v_pk_mul_f32 v[36:37], v[36:37], v[36:37]
	v_pk_mul_f32 v[38:39], v[38:39], v[38:39]
	v_pk_add_f32 v[32:33], v[32:33], v[114:115]
	v_pk_add_f32 v[34:35], v[34:35], v[116:117]
	v_max_f32_e32 v32, 0, v32
	v_max_f32_e32 v33, 0, v33
	v_max_f32_e32 v34, 0, v34
	v_max_f32_e32 v35, 0, v35
	v_pk_mul_f32 v[32:33], v[32:33], v[32:33]
	v_pk_mul_f32 v[34:35], v[34:35], v[34:35]
	v_cvt_pk_bf16_f32 v174, v36, v37
	v_cvt_pk_bf16_f32 v175, v38, v39
	v_cvt_pk_bf16_f32 v176, v32, v33
	v_cvt_pk_bf16_f32 v177, v34, v35
	ds_write_b128 v186, v[174:177] offset:8704
	s_waitcnt lgkmcnt(1)
	global_store_dwordx4 v[190:191], v[178:181], off
	s_waitcnt lgkmcnt(0)
	s_barrier
	ds_read_b128 v[182:185], v187 offset:8704
	v_pk_add_f32 v[28:29], v[28:29], v[126:127]
	v_pk_add_f32 v[30:31], v[30:31], v[128:129]
	v_max_f32_e32 v28, 0, v28
	v_max_f32_e32 v29, 0, v29
	v_max_f32_e32 v30, 0, v30
	v_max_f32_e32 v31, 0, v31
	v_pk_mul_f32 v[28:29], v[28:29], v[28:29]
	v_pk_mul_f32 v[30:31], v[30:31], v[30:31]
	v_pk_add_f32 v[24:25], v[24:25], v[122:123]
	v_pk_add_f32 v[26:27], v[26:27], v[124:125]
	v_max_f32_e32 v24, 0, v24
	v_max_f32_e32 v25, 0, v25
	v_max_f32_e32 v26, 0, v26
	v_max_f32_e32 v27, 0, v27
	v_pk_mul_f32 v[24:25], v[24:25], v[24:25]
	v_pk_mul_f32 v[26:27], v[26:27], v[26:27]
	v_cvt_pk_bf16_f32 v174, v28, v29
	v_cvt_pk_bf16_f32 v175, v30, v31
	v_cvt_pk_bf16_f32 v176, v24, v25
	v_cvt_pk_bf16_f32 v177, v26, v27
	ds_write_b128 v186, v[174:177]
	s_waitcnt lgkmcnt(1)
	global_store_dwordx4 v[190:191], v[182:185], off offset:256
	s_waitcnt lgkmcnt(0)
	s_barrier
	ds_read_b128 v[178:181], v187
	s_mov_b32 s98, 0x280000
	v_lshl_add_u64 v[190:191], v[188:189], 0, s[98:99]
	v_pk_add_f32 v[20:21], v[20:21], v[118:119]
	v_pk_add_f32 v[22:23], v[22:23], v[120:121]
	v_max_f32_e32 v20, 0, v20
	v_max_f32_e32 v21, 0, v21
	v_max_f32_e32 v22, 0, v22
	v_max_f32_e32 v23, 0, v23
	v_pk_mul_f32 v[20:21], v[20:21], v[20:21]
	v_pk_mul_f32 v[22:23], v[22:23], v[22:23]
	v_pk_add_f32 v[16:17], v[16:17], v[114:115]
	v_pk_add_f32 v[18:19], v[18:19], v[116:117]
	v_max_f32_e32 v16, 0, v16
	v_max_f32_e32 v17, 0, v17
	v_max_f32_e32 v18, 0, v18
	v_max_f32_e32 v19, 0, v19
	v_pk_mul_f32 v[16:17], v[16:17], v[16:17]
	v_pk_mul_f32 v[18:19], v[18:19], v[18:19]
	v_cvt_pk_bf16_f32 v174, v20, v21
	v_cvt_pk_bf16_f32 v175, v22, v23
	v_cvt_pk_bf16_f32 v176, v16, v17
	v_cvt_pk_bf16_f32 v177, v18, v19
	ds_write_b128 v186, v[174:177] offset:8704
	s_waitcnt lgkmcnt(1)
	global_store_dwordx4 v[190:191], v[178:181], off
	s_waitcnt lgkmcnt(0)
	s_barrier
	ds_read_b128 v[182:185], v187 offset:8704
	v_pk_add_f32 v[12:13], v[12:13], v[126:127]
	v_pk_add_f32 v[14:15], v[14:15], v[128:129]
	v_max_f32_e32 v12, 0, v12
	v_max_f32_e32 v13, 0, v13
	v_max_f32_e32 v14, 0, v14
	v_max_f32_e32 v15, 0, v15
	v_pk_mul_f32 v[12:13], v[12:13], v[12:13]
	v_pk_mul_f32 v[14:15], v[14:15], v[14:15]
	v_pk_add_f32 v[8:9], v[8:9], v[122:123]
	v_pk_add_f32 v[10:11], v[10:11], v[124:125]
	v_max_f32_e32 v8, 0, v8
	v_max_f32_e32 v9, 0, v9
	v_max_f32_e32 v10, 0, v10
	v_max_f32_e32 v11, 0, v11
	v_pk_mul_f32 v[8:9], v[8:9], v[8:9]
	v_pk_mul_f32 v[10:11], v[10:11], v[10:11]
	v_cvt_pk_bf16_f32 v174, v12, v13
	v_cvt_pk_bf16_f32 v175, v14, v15
	v_cvt_pk_bf16_f32 v176, v8, v9
	v_cvt_pk_bf16_f32 v177, v10, v11
	ds_write_b128 v186, v[174:177]
	s_waitcnt lgkmcnt(1)
	global_store_dwordx4 v[190:191], v[182:185], off offset:256
	s_waitcnt lgkmcnt(0)
	s_barrier
	ds_read_b128 v[178:181], v187
	s_mov_b32 s98, 0x2c0000
	v_lshl_add_u64 v[190:191], v[188:189], 0, s[98:99]
	v_pk_add_f32 v[4:5], v[4:5], v[118:119]
	v_pk_add_f32 v[6:7], v[6:7], v[120:121]
	v_max_f32_e32 v4, 0, v4
	v_max_f32_e32 v5, 0, v5
	v_max_f32_e32 v6, 0, v6
	v_max_f32_e32 v7, 0, v7
	v_pk_mul_f32 v[4:5], v[4:5], v[4:5]
	v_pk_mul_f32 v[6:7], v[6:7], v[6:7]
	v_pk_add_f32 v[0:1], v[0:1], v[114:115]
	v_pk_add_f32 v[2:3], v[2:3], v[116:117]
	v_max_f32_e32 v0, 0, v0
	v_max_f32_e32 v1, 0, v1
	v_max_f32_e32 v2, 0, v2
	v_max_f32_e32 v3, 0, v3
	v_pk_mul_f32 v[0:1], v[0:1], v[0:1]
	v_pk_mul_f32 v[2:3], v[2:3], v[2:3]
	v_cvt_pk_bf16_f32 v174, v4, v5
	v_cvt_pk_bf16_f32 v175, v6, v7
	v_cvt_pk_bf16_f32 v176, v0, v1
	v_cvt_pk_bf16_f32 v177, v2, v3
	ds_write_b128 v186, v[174:177] offset:8704
	s_waitcnt lgkmcnt(1)
	global_store_dwordx4 v[190:191], v[178:181], off
	s_waitcnt lgkmcnt(0)
	s_barrier
	ds_read_b128 v[182:185], v187 offset:8704
	s_waitcnt lgkmcnt(0)
	global_store_dwordx4 v[190:191], v[182:185], off offset:256
	s_and_b64 vcc, exec, s[26:27]
	s_mov_b64 s[36:37], s[24:25]
	s_cbranch_vccnz .LBB0_861

; __device__ __forceinline__ unsigned pk2(float lo, float hi) { const v2f_t f = {lo, hi}; const v2bf_t b = __builtin_convertvector(f, v2bf_t); return __builtin_bit_cast(unsigned, b); }
;     __device__ __forceinline__ void operator()(const f32x4 (&acc)[2][2][4][2], const Unit& u, int wr, int wc, int fr, int fq) const {
;     ...
;         for (int ai = 0; ai < 2; ++ai)
; #pragma unroll
;             for (int m = 0; m < 4; ++m) { bf16_t* rowp = delta + (size_t)(row0 + ai * 128 + m * 16) * D + col0;
; #pragma unroll
;                 for (int bj = 0; bj < 2; ++bj) { const f32x4 v0 = gv[bj][0] * (acc[ai][bj][m][0] + bv[bj][0]), v1 = gv[bj][1] * (acc[ai][bj][m][1] + bv[bj][1]);
;                     u32x4 w; w.x = pk2(v0[0], v0[1]); w.y = pk2(v0[2], v0[3]); w.z = pk2(v1[0], v1[1]); w.w = pk2(v1[2], v1[3]);
;                     *(u32x4*)(rowp + bj * 128) = w; } }
.LBB0_973:
	v_and_b32_e32 v183, 15, v194
	v_bfe_u32 v184, v194, 6, 2
	v_bfe_u32 v185, v194, 4, 2
	v_bfe_u32 v218, v194, 8, 1
	v_lshlrev_b32_e32 v218, 4, v218
	v_add_u32_e32 v218, v218, v183
	v_mul_u32_u24_e32 v212, 0x110, v218
	v_lshl_add_u32 v212, v184, 6, v212
	v_lshl_add_u32 v212, v185, 4, v212
	v_add_u32_e32 v212, 0x23410, v212
	v_lshrrev_b32_e32 v218, 6, v194
	v_lshl_add_u32 v218, v218, 2, v185
	v_mul_u32_u24_e32 v213, 0x110, v218
	v_lshl_add_u32 v213, v183, 4, v213
	v_add_u32_e32 v213, 0x23410, v213
	v_sub_u32_e32 v218, v182, v183
	v_lshl_add_u32 v218, v184, 2, v218
	v_add_u32_e32 v218, v218, v185
	v_lshlrev_b32_e32 v218, 12, v218
	v_and_b32_e32 v219, 0xffffff00, v180
	v_lshlrev_b32_e32 v219, 1, v219
	v_lshl_add_u32 v219, v183, 4, v219
	v_add_u32_e32 v218, v218, v219
	v_mov_b32_e32 v219, 0
	v_lshl_add_u64 v[214:215], s[2:3], 0, v[218:219]
	s_mov_b32 s11, 0
	s_mov_b64 s[20:21], 0
	s_waitcnt vmcnt(0)
	v_pk_add_f32 v[126:127], v[126:127], v[138:139]
	v_pk_add_f32 v[128:129], v[128:129], v[140:141]
	v_pk_mul_f32 v[126:127], v[134:135], v[126:127]
	v_pk_mul_f32 v[128:129], v[136:137], v[128:129]
	v_pk_add_f32 v[122:123], v[122:123], v[130:131]
	v_pk_add_f32 v[124:125], v[124:125], v[132:133]
	v_pk_mul_f32 v[122:123], v[142:143], v[122:123]
	v_pk_mul_f32 v[124:125], v[144:145], v[124:125]
	v_cvt_pk_bf16_f32 v190, v126, v127
	v_cvt_pk_bf16_f32 v191, v128, v129
	v_cvt_pk_bf16_f32 v192, v122, v123
	v_cvt_pk_bf16_f32 v193, v124, v125
	ds_write_b128 v212, v[190:193]
	s_waitcnt lgkmcnt(0)
	s_barrier
	ds_read_b128 v[204:207], v213
	s_mov_b32 s10, 0x0
	v_lshl_add_u64 v[216:217], v[214:215], 0, s[10:11]
	v_pk_add_f32 v[118:119], v[118:119], v[154:155]
	v_pk_add_f32 v[120:121], v[120:121], v[156:157]
	v_pk_mul_f32 v[118:119], v[150:151], v[118:119]
	v_pk_mul_f32 v[120:121], v[152:153], v[120:121]
	v_pk_add_f32 v[114:115], v[114:115], v[146:147]
	v_pk_add_f32 v[116:117], v[116:117], v[148:149]
	v_pk_mul_f32 v[114:115], v[158:159], v[114:115]
	v_pk_mul_f32 v[116:117], v[160:161], v[116:117]
	v_cvt_pk_bf16_f32 v190, v118, v119
	v_cvt_pk_bf16_f32 v191, v120, v121
	v_cvt_pk_bf16_f32 v192, v114, v115
	v_cvt_pk_bf16_f32 v193, v116, v117
	ds_write_b128 v212, v[190:193] offset:8704
	s_waitcnt lgkmcnt(1)
	global_store_dwordx4 v[216:217], v[204:207], off
	s_waitcnt lgkmcnt(0)
	s_barrier
	ds_read_b128 v[208:211], v213 offset:8704
	v_pk_add_f32 v[110:111], v[110:111], v[138:139]
	v_pk_add_f32 v[112:113], v[112:113], v[140:141]
	v_pk_mul_f32 v[110:111], v[134:135], v[110:111]
	v_pk_mul_f32 v[112:113], v[136:137], v[112:113]
	v_pk_add_f32 v[106:107], v[106:107], v[130:131]
	v_pk_add_f32 v[108:109], v[108:109], v[132:133]
	v_pk_mul_f32 v[106:107], v[142:143], v[106:107]
	v_pk_mul_f32 v[108:109], v[144:145], v[108:109]
	v_cvt_pk_bf16_f32 v190, v110, v111
	v_cvt_pk_bf16_f32 v191, v112, v113
	v_cvt_pk_bf16_f32 v192, v106, v107
	v_cvt_pk_bf16_f32 v193, v108, v109
	ds_write_b128 v212, v[190:193]
	s_waitcnt lgkmcnt(1)
	global_store_dwordx4 v[216:217], v[208:211], off offset:256
	s_waitcnt lgkmcnt(0)
	s_barrier
	ds_read_b128 v[204:207], v213
	s_mov_b32 s10, 0x10000
	v_lshl_add_u64 v[216:217], v[214:215], 0, s[10:11]
	v_pk_add_f32 v[102:103], v[102:103], v[154:155]
	v_pk_add_f32 v[104:105], v[104:105], v[156:157]
	v_pk_mul_f32 v[102:103], v[150:151], v[102:103]
	v_pk_mul_f32 v[104:105], v[152:153], v[104:105]
	v_pk_add_f32 v[98:99], v[98:99], v[146:147]
	v_pk_add_f32 v[100:101], v[100:101], v[148:149]
	v_pk_mul_f32 v[98:99], v[158:159], v[98:99]
	v_pk_mul_f32 v[100:101], v[160:161], v[100:101]
	v_cvt_pk_bf16_f32 v190, v102, v103
	v_cvt_pk_bf16_f32 v191, v104, v105
	v_cvt_pk_bf16_f32 v192, v98, v99
	v_cvt_pk_bf16_f32 v193, v100, v101
	ds_write_b128 v212, v[190:193] offset:8704
	s_waitcnt lgkmcnt(1)
	global_store_dwordx4 v[216:217], v[204:207], off
	s_waitcnt lgkmcnt(0)
	s_barrier
	ds_read_b128 v[208:211], v213 offset:8704
	v_pk_add_f32 v[94:95], v[94:95], v[138:139]
	v_pk_add_f32 v[96:97], v[96:97], v[140:141]
	v_pk_mul_f32 v[94:95], v[134:135], v[94:95]
	v_pk_mul_f32 v[96:97], v[136:137], v[96:97]
	v_pk_add_f32 v[90:91], v[90:91], v[130:131]
	v_pk_add_f32 v[92:93], v[92:93], v[132:133]
	v_pk_mul_f32 v[90:91], v[142:143], v[90:91]
	v_pk_mul_f32 v[92:93], v[144:145], v[92:93]
	v_cvt_pk_bf16_f32 v190, v94, v95
	v_cvt_pk_bf16_f32 v191, v96, v97
	v_cvt_pk_bf16_f32 v192, v90, v91
	v_cvt_pk_bf16_f32 v193, v92, v93
	ds_write_b128 v212, v[190:193]
	s_waitcnt lgkmcnt(1)
	global_store_dwordx4 v[216:217], v[208:211], off offset:256
	s_waitcnt lgkmcnt(0)
	s_barrier
	ds_read_b128 v[204:207], v213
	s_mov_b32 s10, 0x20000
	v_lshl_add_u64 v[216:217], v[214:215], 0, s[10:11]
	v_pk_add_f32 v[86:87], v[86:87], v[154:155]
	v_pk_add_f32 v[88:89], v[88:89], v[156:157]
	v_pk_mul_f32 v[86:87], v[150:151], v[86:87]
	v_pk_mul_f32 v[88:89], v[152:153], v[88:89]
	v_pk_add_f32 v[82:83], v[82:83], v[146:147]
	v_pk_add_f32 v[84:85], v[84:85], v[148:149]
	v_pk_mul_f32 v[82:83], v[158:159], v[82:83]
	v_pk_mul_f32 v[84:85], v[160:161], v[84:85]
	v_cvt_pk_bf16_f32 v190, v86, v87
	v_cvt_pk_bf16_f32 v191, v88, v89
	v_cvt_pk_bf16_f32 v192, v82, v83
	v_cvt_pk_bf16_f32 v193, v84, v85
	ds_write_b128 v212, v[190:193] offset:8704
	s_waitcnt lgkmcnt(1)
	global_store_dwordx4 v[216:217], v[204:207], off
	s_waitcnt lgkmcnt(0)
	s_barrier
	ds_read_b128 v[208:211], v213 offset:8704
	v_pk_add_f32 v[78:79], v[78:79], v[138:139]
	v_pk_add_f32 v[80:81], v[80:81], v[140:141]
	v_pk_mul_f32 v[78:79], v[134:135], v[78:79]
	v_pk_mul_f32 v[80:81], v[136:137], v[80:81]
	v_pk_add_f32 v[74:75], v[74:75], v[130:131]
	v_pk_add_f32 v[76:77], v[76:77], v[132:133]
	v_pk_mul_f32 v[74:75], v[142:143], v[74:75]
	v_pk_mul_f32 v[76:77], v[144:145], v[76:77]
	v_cvt_pk_bf16_f32 v190, v78, v79
	v_cvt_pk_bf16_f32 v191, v80, v81
	v_cvt_pk_bf16_f32 v192, v74, v75
	v_cvt_pk_bf16_f32 v193, v76, v77
	ds_write_b128 v212, v[190:193]
	s_waitcnt lgkmcnt(1)
	global_store_dwordx4 v[216:217], v[208:211], off offset:256
	s_waitcnt lgkmcnt(0)
	s_barrier
; __device__ __forceinline__ unsigned pk2(float lo, float hi) { const v2f_t f = {lo, hi}; const v2bf_t b = __builtin_convertvector(f, v2bf_t); return __builtin_bit_cast(unsigned, b); }
;     __device__ __forceinline__ void operator()(const f32x4 (&acc)[2][2][4][2], const Unit& u, int wr, int wc, int fr, int fq) const {
;     ...
;         for (int ai = 0; ai < 2; ++ai)
; #pragma unroll
;             for (int m = 0; m < 4; ++m) { bf16_t* rowp = delta + (size_t)(row0 + ai * 128 + m * 16) * D + col0;
; #pragma unroll
;                 for (int bj = 0; bj < 2; ++bj) { const f32x4 v0 = gv[bj][0] * (acc[ai][bj][m][0] + bv[bj][0]), v1 = gv[bj][1] * (acc[ai][bj][m][1] + bv[bj][1]);
;                     u32x4 w; w.x = pk2(v0[0], v0[1]); w.y = pk2(v0[2], v0[3]); w.z = pk2(v1[0], v1[1]); w.w = pk2(v1[2], v1[3]);
;                     *(u32x4*)(rowp + bj * 128) = w; } }
	ds_read_b128 v[204:207], v213
	s_mov_b32 s10, 0x30000
	v_lshl_add_u64 v[216:217], v[214:215], 0, s[10:11]
	v_pk_add_f32 v[70:71], v[70:71], v[154:155]
	v_pk_add_f32 v[72:73], v[72:73], v[156:157]
	v_pk_mul_f32 v[70:71], v[150:151], v[70:71]
	v_pk_mul_f32 v[72:73], v[152:153], v[72:73]
	v_pk_add_f32 v[66:67], v[66:67], v[146:147]
	v_pk_add_f32 v[68:69], v[68:69], v[148:149]
	v_pk_mul_f32 v[66:67], v[158:159], v[66:67]
	v_pk_mul_f32 v[68:69], v[160:161], v[68:69]
	v_cvt_pk_bf16_f32 v190, v70, v71
	v_cvt_pk_bf16_f32 v191, v72, v73
	v_cvt_pk_bf16_f32 v192, v66, v67
	v_cvt_pk_bf16_f32 v193, v68, v69
	ds_write_b128 v212, v[190:193] offset:8704
	s_waitcnt lgkmcnt(1)
	global_store_dwordx4 v[216:217], v[204:207], off
	s_waitcnt lgkmcnt(0)
	s_barrier
	ds_read_b128 v[208:211], v213 offset:8704
	v_pk_add_f32 v[60:61], v[60:61], v[138:139]
	v_pk_add_f32 v[62:63], v[62:63], v[140:141]
	v_pk_mul_f32 v[60:61], v[134:135], v[60:61]
	v_pk_mul_f32 v[62:63], v[136:137], v[62:63]
	v_pk_add_f32 v[56:57], v[56:57], v[130:131]
	v_pk_add_f32 v[58:59], v[58:59], v[132:133]
	v_pk_mul_f32 v[56:57], v[142:143], v[56:57]
	v_pk_mul_f32 v[58:59], v[144:145], v[58:59]
	v_cvt_pk_bf16_f32 v190, v60, v61
	v_cvt_pk_bf16_f32 v191, v62, v63
	v_cvt_pk_bf16_f32 v192, v56, v57
	v_cvt_pk_bf16_f32 v193, v58, v59
	ds_write_b128 v212, v[190:193]
	s_waitcnt lgkmcnt(1)
	global_store_dwordx4 v[216:217], v[208:211], off offset:256
	s_waitcnt lgkmcnt(0)
	s_barrier
	ds_read_b128 v[204:207], v213
	s_mov_b32 s10, 0x80000
	v_lshl_add_u64 v[216:217], v[214:215], 0, s[10:11]
	v_pk_add_f32 v[52:53], v[52:53], v[154:155]
	v_pk_add_f32 v[54:55], v[54:55], v[156:157]
	v_pk_mul_f32 v[52:53], v[150:151], v[52:53]
	v_pk_mul_f32 v[54:55], v[152:153], v[54:55]
	v_pk_add_f32 v[48:49], v[48:49], v[146:147]
	v_pk_add_f32 v[50:51], v[50:51], v[148:149]
	v_pk_mul_f32 v[48:49], v[158:159], v[48:49]
	v_pk_mul_f32 v[50:51], v[160:161], v[50:51]
	v_cvt_pk_bf16_f32 v190, v52, v53
	v_cvt_pk_bf16_f32 v191, v54, v55
	v_cvt_pk_bf16_f32 v192, v48, v49
	v_cvt_pk_bf16_f32 v193, v50, v51
	ds_write_b128 v212, v[190:193] offset:8704
	s_waitcnt lgkmcnt(1)
	global_store_dwordx4 v[216:217], v[204:207], off
	s_waitcnt lgkmcnt(0)
	s_barrier
	ds_read_b128 v[208:211], v213 offset:8704
	v_pk_add_f32 v[44:45], v[44:45], v[138:139]
	v_pk_add_f32 v[46:47], v[46:47], v[140:141]
	v_pk_mul_f32 v[44:45], v[134:135], v[44:45]
	v_pk_mul_f32 v[46:47], v[136:137], v[46:47]
	v_pk_add_f32 v[40:41], v[40:41], v[130:131]
	v_pk_add_f32 v[42:43], v[42:43], v[132:133]
	v_pk_mul_f32 v[40:41], v[142:143], v[40:41]
	v_pk_mul_f32 v[42:43], v[144:145], v[42:43]
	v_cvt_pk_bf16_f32 v190, v44, v45
	v_cvt_pk_bf16_f32 v191, v46, v47
	v_cvt_pk_bf16_f32 v192, v40, v41
	v_cvt_pk_bf16_f32 v193, v42, v43
	ds_write_b128 v212, v[190:193]
	s_waitcnt lgkmcnt(1)
	global_store_dwordx4 v[216:217], v[208:211], off offset:256
	s_waitcnt lgkmcnt(0)
	s_barrier
	ds_read_b128 v[204:207], v213
	s_mov_b32 s10, 0x90000
	v_lshl_add_u64 v[216:217], v[214:215], 0, s[10:11]
	v_pk_add_f32 v[36:37], v[36:37], v[154:155]
	v_pk_add_f32 v[38:39], v[38:39], v[156:157]
	v_pk_mul_f32 v[36:37], v[150:151], v[36:37]
	v_pk_mul_f32 v[38:39], v[152:153], v[38:39]
	v_pk_add_f32 v[32:33], v[32:33], v[146:147]
	v_pk_add_f32 v[34:35], v[34:35], v[148:149]
	v_pk_mul_f32 v[32:33], v[158:159], v[32:33]
	v_pk_mul_f32 v[34:35], v[160:161], v[34:35]
	v_cvt_pk_bf16_f32 v190, v36, v37
	v_cvt_pk_bf16_f32 v191, v38, v39
	v_cvt_pk_bf16_f32 v192, v32, v33
	v_cvt_pk_bf16_f32 v193, v34, v35
	ds_write_b128 v212, v[190:193] offset:8704
	s_waitcnt lgkmcnt(1)
	global_store_dwordx4 v[216:217], v[204:207], off
	s_waitcnt lgkmcnt(0)
	s_barrier
	ds_read_b128 v[208:211], v213 offset:8704
	v_pk_add_f32 v[28:29], v[28:29], v[138:139]
	v_pk_add_f32 v[30:31], v[30:31], v[140:141]
	v_pk_mul_f32 v[28:29], v[134:135], v[28:29]
	v_pk_mul_f32 v[30:31], v[136:137], v[30:31]
	v_pk_add_f32 v[24:25], v[24:25], v[130:131]
	v_pk_add_f32 v[26:27], v[26:27], v[132:133]
	v_pk_mul_f32 v[24:25], v[142:143], v[24:25]
	v_pk_mul_f32 v[26:27], v[144:145], v[26:27]
	v_cvt_pk_bf16_f32 v190, v28, v29
	v_cvt_pk_bf16_f32 v191, v30, v31
	v_cvt_pk_bf16_f32 v192, v24, v25
	v_cvt_pk_bf16_f32 v193, v26, v27
	ds_write_b128 v212, v[190:193]
	s_waitcnt lgkmcnt(1)
	global_store_dwordx4 v[216:217], v[208:211], off offset:256
	s_waitcnt lgkmcnt(0)
	s_barrier
	ds_read_b128 v[204:207], v213
	s_mov_b32 s10, 0xa0000
	v_lshl_add_u64 v[216:217], v[214:215], 0, s[10:11]
	v_pk_add_f32 v[20:21], v[20:21], v[154:155]
	v_pk_add_f32 v[22:23], v[22:23], v[156:157]
	v_pk_mul_f32 v[20:21], v[150:151], v[20:21]
	v_pk_mul_f32 v[22:23], v[152:153], v[22:23]
	v_pk_add_f32 v[16:17], v[16:17], v[146:147]
	v_pk_add_f32 v[18:19], v[18:19], v[148:149]
	v_pk_mul_f32 v[16:17], v[158:159], v[16:17]
	v_pk_mul_f32 v[18:19], v[160:161], v[18:19]
	v_cvt_pk_bf16_f32 v190, v20, v21
	v_cvt_pk_bf16_f32 v191, v22, v23
	v_cvt_pk_bf16_f32 v192, v16, v17
	v_cvt_pk_bf16_f32 v193, v18, v19
	ds_write_b128 v212, v[190:193] offset:8704
	s_waitcnt lgkmcnt(1)
	global_store_dwordx4 v[216:217], v[204:207], off
	s_waitcnt lgkmcnt(0)
	s_barrier
	ds_read_b128 v[208:211], v213 offset:8704
	v_pk_add_f32 v[12:13], v[12:13], v[138:139]
	v_pk_add_f32 v[14:15], v[14:15], v[140:141]
	v_pk_mul_f32 v[12:13], v[134:135], v[12:13]
	v_pk_mul_f32 v[14:15], v[136:137], v[14:15]
	v_pk_add_f32 v[8:9], v[8:9], v[130:131]
	v_pk_add_f32 v[10:11], v[10:11], v[132:133]
	v_pk_mul_f32 v[8:9], v[142:143], v[8:9]
	v_pk_mul_f32 v[10:11], v[144:145], v[10:11]
	v_cvt_pk_bf16_f32 v190, v12, v13
	v_cvt_pk_bf16_f32 v191, v14, v15
	v_cvt_pk_bf16_f32 v192, v8, v9
	v_cvt_pk_bf16_f32 v193, v10, v11
	ds_write_b128 v212, v[190:193]
	s_waitcnt lgkmcnt(1)
	global_store_dwordx4 v[216:217], v[208:211], off offset:256
	s_waitcnt lgkmcnt(0)
	s_barrier
	ds_read_b128 v[204:207], v213
	s_mov_b32 s10, 0xb0000
	v_lshl_add_u64 v[216:217], v[214:215], 0, s[10:11]
	v_pk_add_f32 v[4:5], v[4:5], v[154:155]
	v_pk_add_f32 v[6:7], v[6:7], v[156:157]
	v_pk_mul_f32 v[4:5], v[150:151], v[4:5]
	v_pk_mul_f32 v[6:7], v[152:153], v[6:7]
	v_pk_add_f32 v[0:1], v[0:1], v[146:147]
	v_pk_add_f32 v[2:3], v[2:3], v[148:149]
	v_pk_mul_f32 v[0:1], v[158:159], v[0:1]
	v_pk_mul_f32 v[2:3], v[160:161], v[2:3]
	v_cvt_pk_bf16_f32 v190, v4, v5
	v_cvt_pk_bf16_f32 v191, v6, v7
	v_cvt_pk_bf16_f32 v192, v0, v1
	v_cvt_pk_bf16_f32 v193, v2, v3
	ds_write_b128 v212, v[190:193] offset:8704
	s_waitcnt lgkmcnt(1)
	global_store_dwordx4 v[216:217], v[204:207], off
	s_waitcnt lgkmcnt(0)
	s_barrier
	ds_read_b128 v[208:211], v213 offset:8704
	s_waitcnt lgkmcnt(0)
	global_store_dwordx4 v[216:217], v[208:211], off offset:256
